# batched LRU look-back aggregate loads (one wait), both SWA Q loads in flight together, on top of prep tile-load unroll and epilogue wait de-serialization
# baseline (speedup 1.0000x reference)
; template <int APPLY>
; __device__ void lru_item(PP p, int l, int bb, int ck, int nb, unsigned epoch) {
;     ...
;       for (;;) {
;         bool ok = true;
; #pragma unroll
;         for (int i = 0; i < 8; ++i) {
;           if (lo + i < hi) {
;             const unsigned long long* src = tg + ((long)(lo + i) * 512 + ch) * 2;
;             wa[i] = __hip_atomic_load(src, __ATOMIC_RELAXED, __HIP_MEMORY_SCOPE_AGENT);
;             wh[i] = __hip_atomic_load(src + 1, __ATOMIC_RELAXED, __HIP_MEMORY_SCOPE_AGENT);
;             ok = ok && ((unsigned)(wa[i] >> 32) == epoch) && ((unsigned)(wh[i] >> 32) == epoch);
;           }
;         }
;         if (ok || ++spins > (1u << 20)) break;
;         __builtin_amdgcn_s_sleep(2);
;       }
.LBB0_126:
	s_mov_b64 s[4:5], exec
	s_and_b64 exec, s[4:5], s[38:39]
	global_load_dwordx2 v[52:53], v[4:5], off sc1
	global_load_dwordx2 v[56:57], v[4:5], off offset:8 sc1
	s_and_b64 exec, s[4:5], s[40:41]
	global_load_dwordx2 v[50:51], v[8:9], off sc1
	global_load_dwordx2 v[54:55], v[8:9], off offset:8 sc1
	s_and_b64 exec, s[4:5], s[42:43]
	global_load_dwordx2 v[42:43], v[14:15], off sc1
	global_load_dwordx2 v[46:47], v[14:15], off offset:8 sc1
	s_and_b64 exec, s[4:5], s[44:45]
	global_load_dwordx2 v[36:37], v[26:27], off sc1
	global_load_dwordx2 v[40:41], v[26:27], off offset:8 sc1
	s_and_b64 exec, s[4:5], s[46:47]
	global_load_dwordx2 v[30:31], v[32:33], off sc1
	global_load_dwordx2 v[34:35], v[32:33], off offset:8 sc1
	s_and_b64 exec, s[4:5], s[48:49]
	global_load_dwordx2 v[24:25], v[38:39], off sc1
	global_load_dwordx2 v[28:29], v[38:39], off offset:8 sc1
	s_and_b64 exec, s[4:5], s[50:51]
	global_load_dwordx2 v[12:13], v[44:45], off sc1
	global_load_dwordx2 v[16:17], v[44:45], off offset:8 sc1
	s_and_b64 exec, s[4:5], s[52:53]
	global_load_dwordx2 v[6:7], v[48:49], off sc1
	global_load_dwordx2 v[10:11], v[48:49], off offset:8 sc1
	s_mov_b64 exec, s[4:5]
	s_waitcnt vmcnt(0)
	v_cmp_eq_u32_e64 s[56:57], s71, v53
	v_cmp_eq_u32_e64 s[58:59], s71, v57
	s_and_b64 s[56:57], s[56:57], s[58:59]
	s_orn2_b64 s[82:83], s[56:57], s[38:39]
	v_cmp_eq_u32_e64 s[56:57], s71, v51
	v_cmp_eq_u32_e64 s[58:59], s71, v55
	s_and_b64 s[56:57], s[56:57], s[58:59]
	s_orn2_b64 s[56:57], s[56:57], s[40:41]
	s_and_b64 s[82:83], s[82:83], s[56:57]
	v_cmp_eq_u32_e64 s[56:57], s71, v43
	v_cmp_eq_u32_e64 s[58:59], s71, v47
	s_and_b64 s[56:57], s[56:57], s[58:59]
	s_orn2_b64 s[56:57], s[56:57], s[42:43]
	s_and_b64 s[82:83], s[82:83], s[56:57]
	v_cmp_eq_u32_e64 s[56:57], s71, v37
	v_cmp_eq_u32_e64 s[58:59], s71, v41
	s_and_b64 s[56:57], s[56:57], s[58:59]
	s_orn2_b64 s[56:57], s[56:57], s[44:45]
	s_and_b64 s[82:83], s[82:83], s[56:57]
	v_cmp_eq_u32_e64 s[56:57], s71, v31
	v_cmp_eq_u32_e64 s[58:59], s71, v35
	s_and_b64 s[56:57], s[56:57], s[58:59]
	s_orn2_b64 s[56:57], s[56:57], s[46:47]
	s_and_b64 s[82:83], s[82:83], s[56:57]
	v_cmp_eq_u32_e64 s[56:57], s71, v25
	v_cmp_eq_u32_e64 s[58:59], s71, v29
	s_and_b64 s[56:57], s[56:57], s[58:59]
	s_orn2_b64 s[56:57], s[56:57], s[48:49]
	s_and_b64 s[82:83], s[82:83], s[56:57]
	v_cmp_eq_u32_e64 s[56:57], s71, v13
	v_cmp_eq_u32_e64 s[58:59], s71, v17
	s_and_b64 s[56:57], s[56:57], s[58:59]
	s_orn2_b64 s[56:57], s[56:57], s[50:51]
	s_and_b64 s[82:83], s[82:83], s[56:57]
	v_cmp_eq_u32_e64 s[56:57], s71, v7
	v_cmp_eq_u32_e64 s[58:59], s71, v11
	s_and_b64 s[56:57], s[56:57], s[58:59]
	s_orn2_b64 s[56:57], s[56:57], s[52:53]
	s_and_b64 s[82:83], s[82:83], s[56:57]

; __device__ __forceinline__ float bflo(unsigned w) { return __uint_as_float(w << 16); }
; __device__ __forceinline__ float bfhi(unsigned w) { return __uint_as_float(w & 0xffff0000u); }
; __device__ __forceinline__ float shx(float v, int mask, int lane) { return __int_as_float(__builtin_amdgcn_ds_bpermute((lane ^ mask) << 2, __float_as_int(v))); }
; template <int D, int MODE>
; __device__ void attn_item(PP p, int c, int l, int bb, int qb0, int h0) {
;     ...
;     const bf16_t* gp0 = p->proj + rowQ * INW + gcol + 4 * fq;
; #pragma unroll
;     for (int d = 0; d < NDS; ++d) gvp[d] = *(const uint2*)(gp0 + d * 16);
;   }
;   bf16x8 qf[NKS];
;   {
;     float qv[NKS][8]; float ss = 0.f;
; #pragma unroll
;     for (int ks = 0; ks < NKS; ++ks) {
;       uint4 u = *(const uint4*)(qptr + ks * 32 + fq * 8);
;       qv[ks][0] = bflo(u.x); qv[ks][1] = bfhi(u.x); qv[ks][2] = bflo(u.y); qv[ks][3] = bfhi(u.y);
;       qv[ks][4] = bflo(u.z); qv[ks][5] = bfhi(u.z); qv[ks][6] = bflo(u.w); qv[ks][7] = bfhi(u.w);
; #pragma unroll
;       for (int i = 0; i < 8; ++i) ss += qv[ks][i] * qv[ks][i];
;     }
;     float rs = sc;
;     const float* qg = (MODE == 0) ? (p->swa_q_gain + l * 64) : (p->mem_q_gain + l * 128);
;     if (MODE != 1) {
;       ss += shx(ss, 16, lane); ss += shx(ss, 32, lane);
;       rs = rsqrtf(ss * (1.0f / D) + EPS) * sc;
;     ...
; #pragma unroll
;       for (int ps = 0; ps < NPK; ++ps)
;         if (ps * RPP < nk) {
;           uint4 u = kreg[ps];
;           if (MODE != 1) {
;             float f[8] = {bflo(u.x), bfhi(u.x), bflo(u.y), bfhi(u.y), bflo(u.z), bfhi(u.z), bflo(u.w), bfhi(u.w)};
;             float ss = 0.f;
; #pragma unroll
;             for (int i = 0; i < 8; ++i) ss += f[i] * f[i];
; #pragma unroll
;             for (int off = 1; off < TPR; off <<= 1) ss += shx(ss, off, lane);
;             const float rs = rsqrtf(ss * (1.0f / D) + EPS);
; #pragma unroll
;             for (int i = 0; i < 8; ++i) f[i] *= rs * kg[cc * 8 + i];
;             u.x = cvt_pk_bf16(f[0], f[1]); u.y = cvt_pk_bf16(f[2], f[3]); u.z = cvt_pk_bf16(f[4], f[5]); u.w = cvt_pk_bf16(f[6], f[7]);
;           }
;           *(uint4*)(Ks + (ps * RPP + trow) * KP + cc * 8) = u;
.LBB0_197:
	s_add_i32 s13, s5, s4
	s_lshl_b32 s92, s13, 7
	v_lshl_add_u64 v[34:35], v[58:59], 0, s[92:93]
	v_mov_b32_e32 v81, v1
	v_lshl_add_u64 v[82:83], v[34:35], 0, v[0:1]
	v_lshl_add_u64 v[38:39], v[34:35], 0, v[80:81]
	global_load_dwordx2 v[90:91], v[82:83], off offset:1536
	global_load_dwordx2 v[88:89], v[82:83], off offset:1568
	global_load_dwordx2 v[86:87], v[82:83], off offset:1600
	global_load_dwordx2 v[84:85], v[82:83], off offset:1632
	global_load_dwordx4 v[34:37], v[38:39], off
	global_load_dwordx4 v[164:167], v[38:39], off offset:64
	s_add_i32 s92, s13, s95
	s_lshl_b64 s[30:31], s[92:93], 2
	s_add_u32 s44, s40, s30
	s_addc_u32 s45, s41, s31
	s_andn2_b64 vcc, exec, s[46:47]
	s_waitcnt vmcnt(1)
	v_lshlrev_b32_e32 v92, 16, v34
	v_and_b32_e32 v93, 0xffff0000, v34
	v_lshlrev_b32_e32 v94, 16, v35
	v_and_b32_e32 v95, 0xffff0000, v35
	v_lshlrev_b32_e32 v96, 16, v36
	v_and_b32_e32 v97, 0xffff0000, v36
	v_lshlrev_b32_e32 v98, 16, v37
	v_and_b32_e32 v99, 0xffff0000, v37
	v_pk_mul_f32 v[134:135], v[92:93], v[92:93]
	v_pk_mul_f32 v[132:133], v[94:95], v[94:95]
	v_add_f32_e32 v81, v134, v135
	v_add_f32_e32 v81, v81, v132
	v_pk_mul_f32 v[130:131], v[96:97], v[96:97]
	v_add_f32_e32 v81, v133, v81
	v_add_f32_e32 v81, v130, v81
	v_pk_mul_f32 v[128:129], v[98:99], v[98:99]
	v_add_f32_e32 v81, v131, v81
	v_add_f32_e32 v81, v128, v81
	v_add_f32_e32 v81, v129, v81
	s_waitcnt vmcnt(0)
	v_lshlrev_b32_e32 v100, 16, v164
	v_and_b32_e32 v101, 0xffff0000, v164
	v_lshlrev_b32_e32 v102, 16, v165
	v_and_b32_e32 v103, 0xffff0000, v165
	v_lshlrev_b32_e32 v104, 16, v166
	v_and_b32_e32 v105, 0xffff0000, v166
	v_lshlrev_b32_e32 v106, 16, v167
	v_and_b32_e32 v107, 0xffff0000, v167
	global_load_dwordx4 v[34:37], v[76:77], off offset:144
	global_load_dwordx4 v[38:41], v[76:77], off offset:128
	global_load_dwordx4 v[42:45], v[76:77], off offset:16
	global_load_dwordx4 v[46:49], v[76:77], off
	global_load_dword v129, v1, s[44:45]
	v_pk_mul_f32 v[56:57], v[100:101], v[100:101]
	v_pk_mul_f32 v[54:55], v[102:103], v[102:103]
	v_add_f32_e32 v56, v56, v81
	v_add_f32_e32 v56, v57, v56
	v_add_f32_e32 v54, v54, v56
	v_pk_mul_f32 v[52:53], v[104:105], v[104:105]
	v_add_f32_e32 v54, v55, v54
	v_add_f32_e32 v52, v52, v54
	v_pk_mul_f32 v[50:51], v[106:107], v[106:107]
	v_add_f32_e32 v52, v53, v52
	v_add_f32_e32 v50, v50, v52
	v_add_f32_e32 v50, v51, v50
	ds_bpermute_b32 v51, v109, v50
	s_waitcnt lgkmcnt(0)
	v_add_f32_e32 v81, v50, v51
	ds_bpermute_b32 v128, v110, v81
	s_cbranch_vccnz .LBB0_203
	s_waitcnt lgkmcnt(0)
	s_barrier
	global_load_dwordx4 v[50:53], v[78:79], off offset:16
	global_load_dwordx4 v[54:57], v[78:79], off
	v_lshlrev_b32_e32 v130, 16, v14
	v_and_b32_e32 v131, 0xffff0000, v14
	v_lshlrev_b32_e32 v146, 16, v22
	v_and_b32_e32 v147, 0xffff0000, v22
	v_lshlrev_b32_e32 v132, 16, v15
	v_and_b32_e32 v133, 0xffff0000, v15
	v_pk_mul_f32 v[144:145], v[130:131], v[130:131]
	v_lshlrev_b32_e32 v148, 16, v23
	v_and_b32_e32 v149, 0xffff0000, v23
	v_pk_mul_f32 v[160:161], v[146:147], v[146:147]
	v_pk_mul_f32 v[142:143], v[132:133], v[132:133]
	v_pk_mul_f32 v[158:159], v[148:149], v[148:149]
	v_mov_b32_e32 v162, v160
	v_mov_b32_e32 v163, v144
	v_mov_b32_e32 v144, v161
	v_lshlrev_b32_e32 v134, 16, v16
	v_and_b32_e32 v135, 0xffff0000, v16
	v_lshlrev_b32_e32 v150, 16, v24
	v_and_b32_e32 v151, 0xffff0000, v24
	v_pk_add_f32 v[144:145], v[162:163], v[144:145]
	v_mov_b32_e32 v160, v158
	v_mov_b32_e32 v161, v142
	v_pk_mul_f32 v[140:141], v[134:135], v[134:135]
	v_pk_mul_f32 v[156:157], v[150:151], v[150:151]
	v_pk_add_f32 v[144:145], v[144:145], v[160:161]
	v_mov_b32_e32 v142, v159
	v_lshlrev_b32_e32 v136, 16, v17
	v_and_b32_e32 v137, 0xffff0000, v17
	v_lshlrev_b32_e32 v152, 16, v25
	v_and_b32_e32 v153, 0xffff0000, v25
	v_pk_add_f32 v[142:143], v[142:143], v[144:145]
	v_mov_b32_e32 v144, v156
	v_mov_b32_e32 v145, v140
	v_pk_mul_f32 v[138:139], v[136:137], v[136:137]
	v_pk_mul_f32 v[154:155], v[152:153], v[152:153]
	v_pk_add_f32 v[142:143], v[144:145], v[142:143]
	v_mov_b32_e32 v140, v157
	v_pk_add_f32 v[140:141], v[140:141], v[142:143]
	v_mov_b32_e32 v142, v154
	v_mov_b32_e32 v143, v138
	v_pk_add_f32 v[140:141], v[142:143], v[140:141]
	v_mov_b32_e32 v138, v155
	v_pk_add_f32 v[138:139], v[138:139], v[140:141]
	ds_bpermute_b32 v141, v115, v139
	ds_bpermute_b32 v140, v115, v138
	s_mov_b32 s30, 0x3c800000
	s_mov_b32 s13, 0x800000
	s_mov_b32 s79, 0x800000
	s_waitcnt lgkmcnt(0)
	v_pk_add_f32 v[138:139], v[138:139], v[140:141]
	ds_bpermute_b32 v141, v116, v139
	ds_bpermute_b32 v140, v116, v138
	s_waitcnt lgkmcnt(0)
	v_pk_add_f32 v[138:139], v[138:139], v[140:141]
	ds_bpermute_b32 v141, v117, v139
	ds_bpermute_b32 v140, v117, v138
	s_waitcnt lgkmcnt(0)
	v_pk_add_f32 v[138:139], v[138:139], v[140:141]
	s_nop 0
	v_pk_fma_f32 v[138:139], v[138:139], s[30:31], v[242:243] op_sel_hi:[1,0,0]
	s_nop 0
	v_mul_f32_e32 v140, 0x4b800000, v139
	v_cmp_gt_f32_e32 vcc, s13, v139
	v_mul_f32_e32 v141, 0x4b800000, v138
	v_cmp_gt_f32_e64 s[38:39], s13, v138
	v_cndmask_b32_e32 v139, v139, v140, vcc
	v_rsq_f32_e32 v139, v139
	v_cndmask_b32_e64 v138, v138, v141, s[38:39]
	v_rsq_f32_e32 v140, v138
	v_mul_f32_e32 v138, 0x45800000, v139
	v_cndmask_b32_e32 v138, v139, v138, vcc
	v_mul_f32_e32 v141, 0x45800000, v140
	s_waitcnt vmcnt(1)
	v_pk_mul_f32 v[154:155], v[50:51], v[138:139] op_sel_hi:[1,0]
	s_waitcnt vmcnt(0)
	v_pk_mul_f32 v[142:143], v[54:55], v[138:139] op_sel_hi:[1,0]
	v_pk_mul_f32 v[144:145], v[56:57], v[138:139] op_sel_hi:[1,0]
	v_pk_mul_f32 v[138:139], v[52:53], v[138:139] op_sel_hi:[1,0]
	v_pk_mul_f32 v[130:131], v[142:143], v[130:131]
	v_pk_mul_f32 v[132:133], v[144:145], v[132:133]
	v_pk_mul_f32 v[134:135], v[154:155], v[134:135]
	v_pk_mul_f32 v[136:137], v[138:139], v[136:137]
	v_cndmask_b32_e64 v140, v140, v141, s[38:39]
	v_cvt_pk_bf16_f32 v130, v130, v131
	v_cvt_pk_bf16_f32 v131, v132, v133
	v_cvt_pk_bf16_f32 v132, v134, v135
	v_cvt_pk_bf16_f32 v133, v136, v137
	v_pk_mul_f32 v[156:157], v[54:55], v[140:141] op_sel_hi:[1,0]
	ds_write_b128 v127, v[130:133]
	v_pk_mul_f32 v[132:133], v[56:57], v[140:141] op_sel_hi:[1,0]
	v_pk_mul_f32 v[134:135], v[50:51], v[140:141] op_sel_hi:[1,0]
	v_pk_mul_f32 v[130:131], v[156:157], v[146:147]
	v_pk_mul_f32 v[132:133], v[132:133], v[148:149]
	v_pk_mul_f32 v[134:135], v[134:135], v[150:151]
	v_pk_mul_f32 v[136:137], v[52:53], v[140:141] op_sel_hi:[1,0]
	v_cvt_pk_bf16_f32 v130, v130, v131
	v_pk_mul_f32 v[136:137], v[136:137], v[152:153]
	v_cvt_pk_bf16_f32 v131, v132, v133
	v_cvt_pk_bf16_f32 v132, v134, v135
	v_cndmask_b32_e64 v134, 0, 1, s[42:43]
	v_cvt_pk_bf16_f32 v133, v136, v137
	v_cmp_ne_u32_e64 s[38:39], 1, v134
	s_andn2_b64 vcc, exec, s[42:43]
	ds_write_b128 v127, v[130:133] offset:9216
	s_cbranch_vccnz .LBB0_200
; __device__ __forceinline__ float bflo(unsigned w) { return __uint_as_float(w << 16); }
; __device__ __forceinline__ float bfhi(unsigned w) { return __uint_as_float(w & 0xffff0000u); }
; __device__ __forceinline__ float shx(float v, int mask, int lane) { return __int_as_float(__builtin_amdgcn_ds_bpermute((lane ^ mask) << 2, __float_as_int(v))); }
; template <int D, int MODE>
; __device__ void attn_item(PP p, int c, int l, int bb, int qb0, int h0) {
;     ...
;       for (int ps = 0; ps < NPK; ++ps)
;         if (ps * RPP < nk) {
;           uint4 u = kreg[ps];
;           if (MODE != 1) {
;             float f[8] = {bflo(u.x), bfhi(u.x), bflo(u.y), bfhi(u.y), bflo(u.z), bfhi(u.z), bflo(u.w), bfhi(u.w)};
;             float ss = 0.f;
; #pragma unroll
;             for (int i = 0; i < 8; ++i) ss += f[i] * f[i];
; #pragma unroll
;             for (int off = 1; off < TPR; off <<= 1) ss += shx(ss, off, lane);
;             const float rs = rsqrtf(ss * (1.0f / D) + EPS);
; #pragma unroll
;             for (int i = 0; i < 8; ++i) f[i] *= rs * kg[cc * 8 + i];
;             u.x = cvt_pk_bf16(f[0], f[1]); u.y = cvt_pk_bf16(f[2], f[3]); u.z = cvt_pk_bf16(f[4], f[5]); u.w = cvt_pk_bf16(f[6], f[7]);
;           }
;           *(uint4*)(Ks + (ps * RPP + trow) * KP + cc * 8) = u;
	v_lshlrev_b32_e32 v130, 16, v10
	v_and_b32_e32 v131, 0xffff0000, v10
	v_lshlrev_b32_e32 v146, 16, v6
	v_and_b32_e32 v147, 0xffff0000, v6
	v_lshlrev_b32_e32 v132, 16, v11
	v_and_b32_e32 v133, 0xffff0000, v11
	v_pk_mul_f32 v[144:145], v[130:131], v[130:131]
	v_lshlrev_b32_e32 v148, 16, v7
	v_and_b32_e32 v149, 0xffff0000, v7
	v_pk_mul_f32 v[160:161], v[146:147], v[146:147]
	v_pk_mul_f32 v[142:143], v[132:133], v[132:133]
	v_pk_mul_f32 v[158:159], v[148:149], v[148:149]
	v_mov_b32_e32 v162, v160
	v_mov_b32_e32 v163, v144
	v_mov_b32_e32 v144, v161
	v_lshlrev_b32_e32 v134, 16, v12
	v_and_b32_e32 v135, 0xffff0000, v12
	v_lshlrev_b32_e32 v150, 16, v8
	v_and_b32_e32 v151, 0xffff0000, v8
	v_pk_add_f32 v[144:145], v[162:163], v[144:145]
	v_mov_b32_e32 v160, v158
	v_mov_b32_e32 v161, v142
	v_pk_mul_f32 v[140:141], v[134:135], v[134:135]
	v_pk_mul_f32 v[156:157], v[150:151], v[150:151]
	v_pk_add_f32 v[144:145], v[144:145], v[160:161]
	v_mov_b32_e32 v142, v159
	v_lshlrev_b32_e32 v136, 16, v13
	v_and_b32_e32 v137, 0xffff0000, v13
	v_lshlrev_b32_e32 v152, 16, v9
	v_and_b32_e32 v153, 0xffff0000, v9
	v_pk_add_f32 v[142:143], v[142:143], v[144:145]
	v_mov_b32_e32 v144, v156
	v_mov_b32_e32 v145, v140
	v_pk_mul_f32 v[138:139], v[136:137], v[136:137]
	v_pk_mul_f32 v[154:155], v[152:153], v[152:153]
	v_pk_add_f32 v[142:143], v[144:145], v[142:143]
	v_mov_b32_e32 v140, v157
	v_pk_add_f32 v[140:141], v[140:141], v[142:143]
	v_mov_b32_e32 v142, v154
	v_mov_b32_e32 v143, v138
	v_pk_add_f32 v[140:141], v[142:143], v[140:141]
	v_mov_b32_e32 v138, v155
	v_pk_add_f32 v[138:139], v[138:139], v[140:141]
	ds_bpermute_b32 v141, v115, v139
	ds_bpermute_b32 v140, v115, v138
	s_waitcnt lgkmcnt(0)
	v_pk_add_f32 v[138:139], v[138:139], v[140:141]
	ds_bpermute_b32 v141, v116, v139
	ds_bpermute_b32 v140, v116, v138
	s_waitcnt lgkmcnt(0)
	v_pk_add_f32 v[138:139], v[138:139], v[140:141]
	ds_bpermute_b32 v141, v117, v139
	ds_bpermute_b32 v140, v117, v138
	s_waitcnt lgkmcnt(0)
	v_pk_add_f32 v[138:139], v[138:139], v[140:141]
	s_nop 0
	v_pk_fma_f32 v[138:139], v[138:139], s[30:31], v[242:243] op_sel_hi:[1,0,0]
	s_nop 0
	v_mul_f32_e32 v140, 0x4b800000, v139
	v_cmp_gt_f32_e32 vcc, s13, v139
	s_nop 1
	v_cndmask_b32_e32 v139, v139, v140, vcc
	v_rsq_f32_e32 v139, v139
	s_nop 0
	v_mul_f32_e32 v140, 0x45800000, v139
	v_cndmask_b32_e32 v140, v139, v140, vcc
	v_pk_mul_f32 v[142:143], v[54:55], v[140:141] op_sel_hi:[1,0]
	v_cmp_gt_f32_e32 vcc, s13, v138
	v_pk_mul_f32 v[130:131], v[142:143], v[130:131]
	v_pk_mul_f32 v[142:143], v[56:57], v[140:141] op_sel_hi:[1,0]
	v_cvt_pk_bf16_f32 v130, v130, v131
	v_pk_mul_f32 v[132:133], v[142:143], v[132:133]
	v_pk_mul_f32 v[142:143], v[50:51], v[140:141] op_sel_hi:[1,0]
	v_cvt_pk_bf16_f32 v131, v132, v133
	v_mul_f32_e32 v132, 0x4b800000, v138
	v_cndmask_b32_e32 v132, v138, v132, vcc
	v_rsq_f32_e32 v138, v132
	v_pk_mul_f32 v[140:141], v[52:53], v[140:141] op_sel_hi:[1,0]
	v_pk_mul_f32 v[134:135], v[142:143], v[134:135]
	v_pk_mul_f32 v[136:137], v[140:141], v[136:137]
	v_cvt_pk_bf16_f32 v132, v134, v135
	v_cvt_pk_bf16_f32 v133, v136, v137
	ds_write_b128 v127, v[130:133] offset:18432
	v_mul_f32_e32 v130, 0x45800000, v138
	v_cndmask_b32_e32 v130, v138, v130, vcc
	v_pk_mul_f32 v[50:51], v[50:51], v[130:131] op_sel_hi:[1,0]
	v_pk_mul_f32 v[54:55], v[54:55], v[130:131] op_sel_hi:[1,0]
	v_pk_mul_f32 v[56:57], v[56:57], v[130:131] op_sel_hi:[1,0]
	v_pk_mul_f32 v[132:133], v[50:51], v[150:151]
	v_pk_mul_f32 v[50:51], v[52:53], v[130:131] op_sel_hi:[1,0]
	v_pk_mul_f32 v[54:55], v[54:55], v[146:147]
	v_pk_mul_f32 v[56:57], v[56:57], v[148:149]
	v_pk_mul_f32 v[130:131], v[50:51], v[152:153]
	v_cvt_pk_bf16_f32 v50, v54, v55
	v_cvt_pk_bf16_f32 v51, v56, v57
	v_cvt_pk_bf16_f32 v52, v132, v133
	v_cvt_pk_bf16_f32 v53, v130, v131
	ds_write_b128 v127, v[50:53] offset:27648
